# diff fast path v4: K-fragment LDS reads issued before the three LDS-DMA pieces, decision at loop top
# baseline (speedup 1.0000x reference)
; DI void diff_pass(const bf16_t* __restrict__ qrow  , const bf16_t* __restrict__ kg, const bf16_t* __restrict__ vg,
;                   int nkt, int q0, float negM2, f32x16 (&O)[4], float& lsum, char* lds) {
;     ...
;         char* st = lds + (kt & 1) * 24576;
;         if (kt + 1 < nkt) {
;             char* st2 = lds + ((kt + 1) & 1) * 24576 + wb;
;             __builtin_amdgcn_global_load_lds((const unsigned*)(kgs + (size_t)(kt + 1) * 64 * 512), (lds_ptr_t)(st2), 16, 0, 0);
;             __builtin_amdgcn_global_load_lds((const unsigned*)(vgs + (kt + 1) * 64), (lds_ptr_t)(st2 + 8192), 16, 0, 0);
;             __builtin_amdgcn_global_load_lds((const unsigned*)(vgs + (size_t)64 * kS + (kt + 1) * 64), (lds_ptr_t)(st2 + 16384), 16, 0, 0);
;         }
;         __builtin_amdgcn_sched_barrier(0);
;         if (kt * 64 <= q0 + 31) {
;             f32x16 Sx[2];
;             {
;                 bf16x8 kf[2][4];
; #pragma unroll
;                 for (int kb = 0; kb < 2; ++kb)
; #pragma unroll
;                     for (int ks = 0; ks < 4; ++ks) kf[kb][ks] = *(const bf16x8*)(st + (32 * kb + l31) * 128 + (((2 * ks + h) ^ f) << 4));
;                 __builtin_amdgcn_sched_barrier(0);
; #pragma unroll
;                 for (int ks = 0; ks < 4; ++ks)
; #pragma unroll
;                     for (int kb = 0; kb < 2; ++kb) Sx[kb] = ks == 0 ? MFMA(kf[kb][0], qf[0], minit) : MFMA(kf[kb][ks], qf[ks], Sx[kb]);
;             }
;             if (kt * 64 + 63 > q0) {
; #pragma unroll
;                 for (int kb = 0; kb < 2; ++kb)
; #pragma unroll
;                     for (int i = 0; i < 16; ++i) {
;                         float p = fexp2(Sx[kb][i]);
;                         const int key = kt * 64 + 32 * kb + (i & 3) + 8 * (i >> 2) + 4 * h;
;                         if (key > qpos) p = 0.f;
;                         lsum += p; Sx[kb][i] = p;
;                     }
;             } else {
;                 float l0 = 0.f, l1 = 0.f;
; #pragma unroll
;                 for (int i = 0; i < 16; ++i) { const float p0 = fexp2(Sx[0][i]), p1 = fexp2(Sx[1][i]); l0 += p0; l1 += p1; Sx[0][i] = p0; Sx[1][i] = p1; }
;                 lsum += l0 + l1;
;             }
;             bf16x8 pf[4];
;             pf[0] = pack8(Sx[0], 0); pf[1] = pack8(Sx[0], 1); pf[2] = pack8(Sx[1], 0); pf[3] = pack8(Sx[1], 1);
;             {
;                 bf16x8 vf[2][4];
; #pragma unroll
.Ldf_fast:
	s_and_b32 s30, 1, s54
	s_cselect_b32 s28, 0x6000, 0
	s_cselect_b32 s30, 0, 0x6000
	v_or_b32_e32 v0, s30, v188
	v_add_u32_e32 v195, v0, v189
	v_add_u32_e32 v194, v0, v190
	v_add_u32_e32 v193, v0, v191
	v_add_u32_e32 v0, v0, v192
	ds_read_b128 v[2:5], v195
	ds_read_b128 v[10:13], v194
	ds_read_b128 v[200:203], v193
	ds_read_b128 v[208:211], v0
	ds_read_b128 v[6:9], v195 offset:4096
	ds_read_b128 v[196:199], v194 offset:4096
	ds_read_b128 v[204:207], v193 offset:4096
	ds_read_b128 v[212:215], v0 offset:4096
	v_add_u32_e32 v112, s28, v187
	v_lshl_add_u64 v[114:115], v[160:161], 0, v[158:159]
	v_lshl_add_u64 v[120:121], v[164:165], 0, v[158:159]
	v_readfirstlane_b32 s28, v112
	s_mov_b32 m0, s28
	v_add_u32_e32 v118, 0x2000, v112
	global_load_lds_dwordx4 v[114:115], off
	s_mov_b64 s[28:29], 0x1b800080
	v_lshl_add_u64 v[116:117], v[120:121], 0, s[28:29]
	v_readfirstlane_b32 s28, v118
	s_mov_b32 m0, s28
	s_mov_b64 s[28:29], 0x1b900080
	v_add_u32_e32 v112, 0x4000, v112
	v_lshl_add_u64 v[120:121], v[120:121], 0, s[28:29]
	v_mov_b32_e32 v14, 0
	v_mov_b32_e32 v15, 0
	global_load_lds_dwordx4 v[116:117], off
	v_readfirstlane_b32 s28, v112
	s_mov_b32 m0, s28
	s_nop 0
	global_load_lds_dwordx4 v[120:121], off
	s_waitcnt lgkmcnt(7)
	v_mfma_f32_32x32x16_bf16 v[96:111], v[2:5], v[140:143], v[16:31]
	s_waitcnt lgkmcnt(6)
	v_mfma_f32_32x32x16_bf16 v[96:111], v[10:13], v[136:139], v[96:111]
	s_waitcnt lgkmcnt(5)
	v_mfma_f32_32x32x16_bf16 v[96:111], v[200:203], v[132:135], v[96:111]
	s_waitcnt lgkmcnt(4)
	v_mfma_f32_32x32x16_bf16 v[96:111], v[208:211], v[128:131], v[96:111]
	s_waitcnt lgkmcnt(3)
	v_mfma_f32_32x32x16_bf16 v[112:127], v[6:9], v[140:143], v[16:31]
	ds_read_b128 v[2:5], v195 offset:8192
	ds_read_b128 v[10:13], v195 offset:12288
	s_waitcnt lgkmcnt(4)
	v_mfma_f32_32x32x16_bf16 v[112:127], v[196:199], v[136:139], v[112:127]
	ds_read_b128 v[200:203], v195 offset:16384
	ds_read_b128 v[208:211], v195 offset:20480
	s_nop 3
	v_exp_f32_e32 v96, v96
	v_exp_f32_e32 v97, v97
	v_add_f32_e32 v14, v14, v96
	v_add_f32_e32 v14, v14, v97
	s_waitcnt lgkmcnt(5)
	v_mfma_f32_32x32x16_bf16 v[112:127], v[204:207], v[132:135], v[112:127]
	v_exp_f32_e32 v98, v98
	v_exp_f32_e32 v99, v99
	v_add_f32_e32 v14, v14, v98
	v_add_f32_e32 v14, v14, v99
	s_waitcnt lgkmcnt(4)
	v_mfma_f32_32x32x16_bf16 v[112:127], v[212:215], v[128:131], v[112:127]
	v_exp_f32_e32 v100, v100
	v_exp_f32_e32 v101, v101
	v_add_f32_e32 v14, v14, v100
	v_add_f32_e32 v14, v14, v101
	v_exp_f32_e32 v102, v102
	v_exp_f32_e32 v103, v103
	v_add_f32_e32 v14, v14, v102
	v_add_f32_e32 v14, v14, v103
	v_cvt_pk_bf16_f32 v96, v96, v97
	v_cvt_pk_bf16_f32 v97, v98, v99
	v_cvt_pk_bf16_f32 v98, v100, v101
	v_cvt_pk_bf16_f32 v99, v102, v103
	s_waitcnt lgkmcnt(3)
	s_nop 0
	v_mfma_f32_32x32x16_bf16 v[80:95], v[2:5], v[96:99], v[80:95]
	ds_read_b128 v[6:9], v194 offset:8192
	ds_read_b128 v[196:199], v194 offset:12288
	ds_read_b128 v[204:207], v194 offset:16384
	ds_read_b128 v[212:215], v194 offset:20480
	v_exp_f32_e32 v104, v104
	v_exp_f32_e32 v105, v105
	v_add_f32_e32 v14, v14, v104
	v_add_f32_e32 v14, v14, v105
	s_waitcnt lgkmcnt(6)
	v_mfma_f32_32x32x16_bf16 v[64:79], v[10:13], v[96:99], v[64:79]
	ds_read_b128 v[2:5], v193 offset:8192
	v_exp_f32_e32 v106, v106
	v_exp_f32_e32 v107, v107
	v_add_f32_e32 v14, v14, v106
	v_add_f32_e32 v14, v14, v107
	s_waitcnt lgkmcnt(6)
	v_mfma_f32_32x32x16_bf16 v[48:63], v[200:203], v[96:99], v[48:63]
	ds_read_b128 v[10:13], v193 offset:12288
	v_exp_f32_e32 v108, v108
	v_exp_f32_e32 v109, v109
	v_add_f32_e32 v14, v14, v108
	v_add_f32_e32 v14, v14, v109
	s_waitcnt lgkmcnt(6)
	v_mfma_f32_32x32x16_bf16 v[32:47], v[208:211], v[96:99], v[32:47]
	ds_read_b128 v[200:203], v193 offset:16384
	v_exp_f32_e32 v110, v110
	v_exp_f32_e32 v111, v111
	v_add_f32_e32 v14, v14, v110
	v_add_f32_e32 v14, v14, v111
	v_cvt_pk_bf16_f32 v104, v104, v105
	v_cvt_pk_bf16_f32 v105, v106, v107
	v_cvt_pk_bf16_f32 v106, v108, v109
	v_cvt_pk_bf16_f32 v107, v110, v111
	s_waitcnt lgkmcnt(6)
	s_nop 0
	v_mfma_f32_32x32x16_bf16 v[80:95], v[6:9], v[104:107], v[80:95]
	ds_read_b128 v[208:211], v193 offset:20480
	v_exp_f32_e32 v112, v112
	v_exp_f32_e32 v113, v113
	v_add_f32_e32 v15, v15, v112
	v_add_f32_e32 v15, v15, v113
	s_waitcnt lgkmcnt(6)
	v_mfma_f32_32x32x16_bf16 v[64:79], v[196:199], v[104:107], v[64:79]
	ds_read_b128 v[6:9], v0 offset:8192
	v_exp_f32_e32 v114, v114
	v_exp_f32_e32 v115, v115
	v_add_f32_e32 v15, v15, v114
	v_add_f32_e32 v15, v15, v115
	s_waitcnt lgkmcnt(6)
	v_mfma_f32_32x32x16_bf16 v[48:63], v[204:207], v[104:107], v[48:63]
	ds_read_b128 v[196:199], v0 offset:12288
	v_exp_f32_e32 v116, v116
	v_exp_f32_e32 v117, v117
	v_add_f32_e32 v15, v15, v116
	v_add_f32_e32 v15, v15, v117
	s_waitcnt lgkmcnt(6)
	v_mfma_f32_32x32x16_bf16 v[32:47], v[212:215], v[104:107], v[32:47]
	ds_read_b128 v[204:207], v0 offset:16384
	v_exp_f32_e32 v118, v118
	v_exp_f32_e32 v119, v119
	v_add_f32_e32 v15, v15, v118
	v_add_f32_e32 v15, v15, v119
	v_cvt_pk_bf16_f32 v112, v112, v113
	v_cvt_pk_bf16_f32 v113, v114, v115
	v_cvt_pk_bf16_f32 v114, v116, v117
	v_cvt_pk_bf16_f32 v115, v118, v119
	s_waitcnt lgkmcnt(6)
	s_nop 0
	v_mfma_f32_32x32x16_bf16 v[80:95], v[2:5], v[112:115], v[80:95]
	ds_read_b128 v[212:215], v0 offset:20480
	v_exp_f32_e32 v120, v120
	v_exp_f32_e32 v121, v121
	v_add_f32_e32 v15, v15, v120
	v_add_f32_e32 v15, v15, v121
	s_waitcnt lgkmcnt(6)
	v_mfma_f32_32x32x16_bf16 v[64:79], v[10:13], v[112:115], v[64:79]
	v_exp_f32_e32 v122, v122
	v_exp_f32_e32 v123, v123
	v_add_f32_e32 v15, v15, v122
	v_add_f32_e32 v15, v15, v123
	s_waitcnt lgkmcnt(5)
	v_mfma_f32_32x32x16_bf16 v[48:63], v[200:203], v[112:115], v[48:63]
	v_exp_f32_e32 v124, v124
	v_exp_f32_e32 v125, v125
	v_add_f32_e32 v15, v15, v124
	v_add_f32_e32 v15, v15, v125
	s_waitcnt lgkmcnt(4)
	v_mfma_f32_32x32x16_bf16 v[32:47], v[208:211], v[112:115], v[32:47]
	v_exp_f32_e32 v126, v126
	v_exp_f32_e32 v127, v127
	v_add_f32_e32 v15, v15, v126
	v_add_f32_e32 v15, v15, v127
	v_cvt_pk_bf16_f32 v120, v120, v121
	v_cvt_pk_bf16_f32 v121, v122, v123
	v_cvt_pk_bf16_f32 v122, v124, v125
	v_cvt_pk_bf16_f32 v123, v126, v127
	v_add_f32_e32 v14, v14, v15
	s_waitcnt lgkmcnt(3)
	v_mfma_f32_32x32x16_bf16 v[80:95], v[6:9], v[120:123], v[80:95]
	v_add_f32_e32 v186, v186, v14
	s_waitcnt lgkmcnt(2)
	v_mfma_f32_32x32x16_bf16 v[64:79], v[196:199], v[120:123], v[64:79]
	s_waitcnt lgkmcnt(1)
	v_mfma_f32_32x32x16_bf16 v[48:63], v[204:207], v[120:123], v[48:63]
	s_waitcnt lgkmcnt(0)
	v_mfma_f32_32x32x16_bf16 v[32:47], v[212:215], v[120:123], v[32:47]
	s_branch .Ldf_join
